# blocks >= 256 defer wconv_in(l+1) until after their out-GEMM tile
# baseline (speedup 1.0000x reference)
; __global__ void __launch_bounds__(NT, 2) fwd_kernel(Params p) {
;   cg::grid_group grid = cg::this_grid();
;   __shared__ __attribute__((aligned(16))) bf16 lds[GEMM_LDS_BF16 + 256];
;   float* sm = (float*)lds;
;   unsigned char* ws = p.ws;
;   Ctx c{p, sm};
;   __shared__ unsigned bar_st[2];
;   if (threadIdx.x == 0) { bar_st[0] = 0u; bar_st[1] = 0u; }
;   __syncthreads();
;   (void)xcd_barrier_post((unsigned*)(ws + WS_BAR), bar_st);
_Z10fwd_kernel6Params:
	s_load_dwordx2 s[88:89], s[0:1], 0xb0
	s_load_dwordx4 s[4:7], s[0:1], 0xa0
	s_mov_b32 s38, s2
	s_add_u32 s2, s0, 0xb8
	s_addc_u32 s3, s1, 0
	v_and_b32_e32 v172, 0x3ff, v0
	v_writelane_b32 v255, 1, 1
	v_writelane_b32 v255, 0, 4
	v_writelane_b32 v255, 0, 5
	s_waitcnt lgkmcnt(0)
	v_writelane_b32 v252, s4, 0
	s_nop 1
	v_writelane_b32 v252, s5, 1
	v_writelane_b32 v252, s6, 2
	v_writelane_b32 v252, s7, 3
	s_load_dwordx8 s[4:11], s[0:1], 0x80
	s_waitcnt lgkmcnt(0)
	v_writelane_b32 v252, s4, 4
	s_nop 1
	v_writelane_b32 v252, s5, 5
	v_writelane_b32 v252, s6, 6
	v_writelane_b32 v252, s7, 7
	v_writelane_b32 v252, s8, 8
	v_writelane_b32 v252, s9, 9
	v_writelane_b32 v252, s10, 10
	v_writelane_b32 v252, s11, 11
	v_writelane_b32 v252, s2, 12
	v_cmp_eq_u32_e64 s[4:5], 0, v172
	s_nop 0
	v_writelane_b32 v252, s3, 13
	s_mov_b64 s[2:3], exec
	v_writelane_b32 v252, s4, 14
	s_nop 1
	v_writelane_b32 v252, s5, 15
	s_and_b64 s[4:5], s[2:3], s[4:5]
	s_mov_b64 exec, s[4:5]
	v_mov_b32_e32 v2, 0
	v_mov_b32_e32 v3, v2
	v_mov_b32_e32 v1, 0x12200
	ds_write_b64 v1, v[2:3]
	s_or_b64 exec, exec, s[2:3]
	s_load_dwordx2 s[40:41], s[0:1], 0xb8
	s_load_dword s23, s[0:1], 0xc0
	s_waitcnt lgkmcnt(0)
	s_barrier
	s_getreg_b32 s6, hwreg(HW_REG_XCC_ID, 0, 4)
	s_mov_b64 s[2:3], exec
	v_readlane_b32 s4, v252, 14
	v_readlane_b32 s5, v252, 15
	s_and_b64 s[4:5], s[2:3], s[4:5]
	s_mov_b64 exec, s[4:5]
	s_cbranch_execz .LBB0_5
	s_mov_b64 s[4:5], exec
	v_mbcnt_lo_u32_b32 v1, s4, 0
	v_mbcnt_hi_u32_b32 v1, s5, v1
	v_cmp_eq_u32_e32 vcc, 0, v1
	s_and_b64 s[8:9], exec, vcc
	s_mov_b64 exec, s[8:9]
	s_cbranch_execz .LBB0_5
	s_lshl_b32 s6, s6, 8
	s_and_b32 s6, s6, 0xf00
	s_bcnt1_i32_b64 s4, s[4:5]
	v_mov_b32_e32 v1, s6
	v_mov_b32_e32 v2, s4
	global_atomic_add v1, v2, s[88:89] offset:1024

; DI int otid() { int t = threadIdx.x; asm volatile("" : "+v"(t)); return t; }
;   DI bf16* WL() const { return (bf16*)(p.ws + WS_WL); }
;   DI bf16* K() const { return (bf16*)(p.ws + WS_K); }
; DI void wconv_t(const float* W, int K, int N, int Npad, bf16* Wt) {
;   const size_t gt = (size_t)blockIdx.x * NT + otid(), gs = (size_t)gridDim.x * NT;
;   const int kc = K >> 3;
;   for (size_t i = gt; i < (size_t)Npad * kc; i += gs) {
;     const int n = (int)(i % Npad), k0 = (int)(i / Npad) * 8;
; DI void phase_wconv_in(const Ctx& c, int l) {
;   const Params& p = c.p; const int li = l >> 1;
;   if ((l & 1) == 0) wconv_t(p.even_w_in + (size_t)li * D * E_EVEN, D, E_EVEN, 2560, c.WL() + WL_IN / 2);
;   else wconv_t(p.odd_w_in + (size_t)li * D * E_ODD, D, E_ODD, 2560, c.WL() + WL_IN / 2);
.LBB0_1075:
	v_readlane_b32 s0, v254, 53
	v_readlane_b32 s1, v254, 54
	s_andn2_b64 vcc, exec, s[0:1]
	s_nop 0
	v_cndmask_b32_e64 v0, 0, 1, s[0:1]
	v_cmp_ne_u32_e64 s[4:5], 1, v0
	s_cbranch_vccnz .LBB0_1088
	v_readlane_b32 s2, v252, 32
	v_readlane_b32 s3, v255, 5
	s_cmp_ge_u32 s2, 0x10000
	s_cbranch_scc0 .Lwc_entry
	s_cmp_eq_u32 s3, 2
	s_cbranch_scc1 .Lwc_entry
	s_mov_b32 s3, 1
	s_nop 0
	v_writelane_b32 v255, s3, 5
	s_branch .LBB0_1088
.Lwc_entry:
	s_add_i32 s0, s86, 1
	s_lshr_b32 s14, s0, 1
	v_readlane_b32 s0, v254, 51
	v_readlane_b32 s1, v254, 52
	s_andn2_b64 vcc, exec, s[0:1]
	s_mov_b64 s[0:1], -1
	s_cbranch_vccnz .LBB0_1083
	v_mov_b32_e32 v2, v172
	v_readlane_b32 s0, v252, 33
	v_readlane_b32 s1, v252, 34
	v_ashrrev_i32_e32 v3, 31, v2
	s_nop 0
	v_lshl_add_u64 v[6:7], s[0:1], 0, v[2:3]
	s_mov_b64 s[0:1], 0x50000
	v_cmp_gt_u64_e32 vcc, s[0:1], v[6:7]
	s_and_saveexec_b64 s[0:1], vcc
	s_cbranch_execz .LBB0_1082
	v_readlane_b32 s6, v252, 12
	v_readlane_b32 s7, v252, 13
	s_load_dword s8, s[6:7], 0x10
	s_mul_i32 s6, s14, 0x9c0000
	v_readlane_b32 s16, v252, 16
	s_mul_hi_u32 s7, s14, 0x9c0000
	v_readlane_b32 s17, v252, 17
	s_add_u32 s6, s16, s6
	s_addc_u32 s7, s17, s7
	s_waitcnt lgkmcnt(0)
	s_lshr_b32 s8, s8, 16
	s_cmp_lg_u32 s8, 0
	s_cselect_b64 s[8:9], -1, 0
	s_cmp_lg_u64 s[8:9], 0
	s_mov_b32 s3, s85
	s_addc_u32 s2, s40, 0
	s_lshl_b64 s[8:9], s[2:3], 8
	s_mov_b64 s[10:11], 0
	v_readlane_b32 s18, v252, 18
	v_readlane_b32 s19, v252, 19
	v_readlane_b32 s20, v252, 20
	v_readlane_b32 s21, v252, 21
	v_readlane_b32 s22, v252, 22
	v_readlane_b32 s23, v252, 23
	v_readlane_b32 s24, v252, 24
	v_readlane_b32 s25, v252, 25
	v_readlane_b32 s26, v252, 26
	v_readlane_b32 s27, v252, 27
	v_readlane_b32 s28, v252, 28
	v_readlane_b32 s29, v252, 29
	v_readlane_b32 s30, v252, 30
	v_readlane_b32 s31, v252, 31
	s_branch .LBB0_1080

;   DI float* MOD() const { return (float*)(p.ws + WS_MOD); }
;   DI float* XC() const { return (float*)(p.ws + WS_XC); }
;   DI bf16* WL() const { return (bf16*)(p.ws + WS_WL); }
;   DI bf16* HY() const { return (bf16*)(p.ws + WS_HY); }
; __global__ void __launch_bounds__(NT, 2) fwd_kernel(Params p) {
;     ...
;     if (l < 3) phase_wconv_in(c, l + 1);
;     mfma_gemm_big(RowPtr{c.HY(), D}, RowPtr{c.WL() + WL_OUT / 2, D}, MLAT, D, D, EpiResid4{p.x, p.ctx, p.out, c.XC(), c.MOD(), l}, lds);
.LBB0_1088:
	v_readlane_b32 s3, v255, 5
	s_cmp_eq_u32 s3, 2
	s_cbranch_scc0 .Lwc_cont
	s_mov_b32 s3, 0
	s_nop 0
	v_writelane_b32 v255, s3, 5
	s_branch .Lwc_sync

;   DI float* MOD() const { return (float*)(p.ws + WS_MOD); }
;   DI float* XC() const { return (float*)(p.ws + WS_XC); }
;   DI bf16* WL() const { return (bf16*)(p.ws + WS_WL); }
;   DI bf16* HY() const { return (bf16*)(p.ws + WS_HY); }
; #define SYNC() do { XcdBarrier b_; b_.bar = (unsigned*)(p.ws + WS_BAR); b_.x = xb_xcc_id(); b_.st = bar_st; xcd_barrier(b_); } while (0)
; __global__ void __launch_bounds__(NT, 2) fwd_kernel(Params p) {
;     ...
;     if (l < 3) phase_wconv_in(c, l + 1);
;     mfma_gemm_big(RowPtr{c.HY(), D}, RowPtr{c.WL() + WL_OUT / 2, D}, MLAT, D, D, EpiResid4{p.x, p.ctx, p.out, c.XC(), c.MOD(), l}, lds);
;     if (rows_out > MLAT)
;       for (int t = blockIdx.x; t < 32; t += gridDim.x)
;         mfma_gemm_tile<0>(RowPtr{c.HY(), D}, RowPtr{c.WL() + WL_OUT / 2, D}, MLAT + (t >> 3) * 128, (t & 7) * 128, D, EpiResid4{p.x, p.ctx, p.out, c.XC(), c.MOD(), l}, lds);
;     SYNC();
.LBB0_1118:
	v_readlane_b32 s3, v255, 5
	s_cmp_eq_u32 s3, 1
	s_cbranch_scc0 .Lwc_sync
	s_mov_b32 s3, 2
	s_nop 0
	v_writelane_b32 v255, s3, 5
	s_branch .Lwc_entry
